# combo4 + XCD-local seams after ph6,7,8,10,11,14,15 (leader skips L2 writeback + cross-XCD arrival when every logical XCD group sits on one XCC; run-time checked)
# speedup vs baseline: 1.0199x; 1.0199x over previous
; #define SEAM(k) do { if (IN((k) + 1)) grid.sync(); } while (0)
; #define SEAM(k) do { if (hi > (k) + 1) { if (lo > hi) grid.sync(); xcd_barrier(bar); } } while (0)
; __global__ void __launch_bounds__(NTHR, 2) hybrid_fwd(Args args) {
;     ...
;     if (IN(1)) { BODY1; if (PROBE_ID == 101) BODY1; SEAM(1); }
.LBB0_187:
	s_cmp_lt_i32 s80, 2
	s_cselect_b64 s[0:1], -1, 0
	s_cmp_gt_i32 s81, 1
	s_cselect_b64 s[2:3], -1, 0
	s_and_b64 s[0:1], s[0:1], s[2:3]
	s_andn2_b64 vcc, exec, s[0:1]
	s_cbranch_vccnz .LBB0_266
	v_readfirstlane_b32 s98, v0
	s_cmp_lt_u32 s98, 64
	s_cbranch_scc0 .Lxl_s1
	s_and_b32 s98, s96, 7
	s_lshl_b32 s98, s98, 2
	s_add_u32 s100, s78, 0x4100
	s_addc_u32 s101, s79, 0
	s_lshl_b32 s99, 1, s73
	s_cmp_eq_u32 s82, 0x100
	s_cbranch_scc1 .Lxl_g
	s_or_b32 s99, s99, 0x30000
.Lxl_g:
	s_mov_b64 exec, 1
	v_mov_b32_e32 v1, s98
	v_mov_b32_e32 v2, s99
	global_atomic_or v1, v2, s[100:101]
	s_mov_b64 exec, -1

.LBB0_266:
	s_cmp_lt_i32 s80, 3
	s_cselect_b64 s[0:1], -1, 0
	s_cmp_gt_i32 s81, 2
	s_cselect_b64 s[2:3], -1, 0
	s_and_b64 s[0:1], s[0:1], s[2:3]
	s_andn2_b64 vcc, exec, s[0:1]
	s_cbranch_vccnz .LBB0_346
	v_readfirstlane_b32 s98, v0
	s_cmp_lt_u32 s98, 64
	s_cbranch_scc0 .Lxl_ok2
	s_and_b32 s98, s96, 7
	s_lshl_b32 s98, s98, 2
	s_add_u32 s100, s78, 0x4100
	s_addc_u32 s101, s79, 0
	s_mov_b64 exec, 1
	v_mov_b32_e32 v1, s98
	global_load_dword v2, v1, s[100:101] sc1
	s_waitcnt vmcnt(0)
	v_readfirstlane_b32 s99, v2
	s_add_i32 s98, s99, -1
	s_and_b32 s98, s98, s99
	s_cmp_eq_u32 s98, 0
	s_cbranch_scc1 .Lxl_ok1
	v_mov_b32_e32 v1, 0
	v_mov_b32_e32 v2, 1
	global_atomic_add v1, v2, s[100:101] offset:32
.Lxl_ok1:
	s_mov_b64 exec, -1
.Lxl_ok2:
	s_and_b32 s0, s82, 7
	s_cmp_lg_u32 s0, 0
	s_mov_b32 s0, s96
	s_cbranch_scc1 .LBB0_269
	s_and_b32 s0, s96, 7
	s_lshr_b32 s1, s82, 3
	s_mul_i32 s0, s1, s0
	s_lshr_b32 s1, s96, 3
	s_add_i32 s0, s0, s1

; __device__ __forceinline__ unsigned xb_ld(unsigned* p)              { return __hip_atomic_load(p, __ATOMIC_RELAXED, __HIP_MEMORY_SCOPE_AGENT); }
; __device__ __forceinline__ unsigned xb_add(unsigned* p, unsigned v) { return __hip_atomic_fetch_add(p, v, __ATOMIC_RELAXED, __HIP_MEMORY_SCOPE_AGENT); }
; #define XB_SPIN(cond, bar) do { unsigned _sp = 0; while (cond) { __builtin_amdgcn_s_sleep(1); \
;     if ((++_sp & 255u) == 0u) { if (xb_ld(&(bar)[XB_TMO])) break; if (_sp > XB_SPIN_CAP) { atomicAdd(&(bar)[XB_TMO], 1u); break; } } } } while (0)
; __device__ __forceinline__ void xcd_barrier(const XcdBarrier& b) {
;     ...
;         if (old + 1u == (gen + 1u) * nloc) {
;             __builtin_amdgcn_fence(__ATOMIC_RELEASE, "agent");
;             asm volatile("s_waitcnt vmcnt(0)" ::: "memory");
;             const unsigned og = xb_add(&bar[XB_TOP], 1u);
;             const unsigned tg = og / nx;
;             if (og + 1u == (tg + 1u) * nx) xb_add(&bar[XB_TOPGEN], 1u);
;             else XB_SPIN(xb_ld(&bar[XB_TOPGEN]) == tg, bar);
;             __builtin_amdgcn_fence(__ATOMIC_ACQUIRE, "agent");
;             xb_add(&bar[XB_XGEN(b.x)], 1u);
;             asm volatile("s_waitcnt vmcnt(0)" ::: "memory");
.LBB0_660:
	s_andn2_saveexec_b64 s[0:1], s[8:9]
	s_cbranch_execz .LBB0_680
	s_mov_b64 s[8:9], exec
	s_add_u32 s100, s78, 0x4120
	s_addc_u32 s101, s79, 0
	v_mov_b32_e32 v2, 0
	global_load_dword v2, v2, s[100:101] sc1
	s_waitcnt vmcnt(0) lgkmcnt(0)
	v_readfirstlane_b32 s100, v2
	s_cmp_eq_u32 s100, 0
	s_cbranch_scc1 .LBB0_677
	buffer_wbl2 sc1
	s_waitcnt lgkmcnt(0)
	s_waitcnt vmcnt(0)
	v_mbcnt_lo_u32_b32 v2, s8, 0
	v_mbcnt_hi_u32_b32 v2, s9, v2
	v_cmp_eq_u32_e32 vcc, 0, v2
	s_and_saveexec_b64 s[10:11], vcc
	s_cbranch_execz .LBB0_663
	s_bcnt1_i32_b64 s0, s[8:9]
	v_mov_b32_e32 v3, 0x7000
	v_mov_b32_e32 v4, s0
	global_atomic_add v3, v3, v4, s[78:79] offset:1024 sc0
